# phase-1 k/v outputs and phase-5 y as ordinary write-back stores instead of nontemporal
# baseline (speedup 1.0000x reference)
.LBB0_240:
	s_andn2_b64 vcc, exec, s[8:9]
	s_cbranch_vccnz .LBB0_242
	v_lshl_add_u64 v[180:181], s[94:95], 0, v[152:153]
	v_ashrrev_i32_e32 v145, 31, v144
	v_cvt_pk_bf16_f32 v178, v126, v127
	v_cvt_pk_bf16_f32 v179, v128, v129
	v_lshl_add_u64 v[180:181], v[144:145], 1, v[180:181]
	v_lshlrev_b32_e32 v134, 2, v147
	global_store_dwordx2 v[180:181], v[178:179], off
	v_and_b32_e32 v145, 0x16c, v144
	v_lshl_add_u64 v[178:179], s[84:85], 0, v[134:135]
	v_lshl_add_u64 v[178:179], v[178:179], 0, v[148:149]
	v_lshlrev_b32_e32 v134, 2, v145
	v_lshl_add_u64 v[178:179], v[178:179], 0, v[134:135]
	global_store_dwordx4 v[178:179], v[126:129], off

.LBB0_248:
	s_andn2_b64 vcc, exec, s[2:3]
	s_cbranch_vccnz .LBB0_250
	v_ashrrev_i32_e32 v145, 31, v144
	v_cvt_pk_bf16_f32 v128, v122, v123
	v_cvt_pk_bf16_f32 v129, v124, v125
	v_lshl_add_u64 v[178:179], v[144:145], 1, v[152:153]
	v_lshlrev_b32_e32 v134, 2, v147
	global_store_dwordx2 v[178:179], v[128:129], off offset:32
	v_and_b32_e32 v127, 0x17c, v126
	v_lshl_add_u64 v[128:129], s[84:85], 0, v[134:135]
	v_lshl_add_u64 v[128:129], v[128:129], 0, v[148:149]
	v_lshlrev_b32_e32 v134, 2, v127
	v_lshl_add_u64 v[128:129], v[128:129], 0, v[134:135]
	global_store_dwordx4 v[128:129], v[122:125], off

.LBB0_254:
	s_andn2_b64 vcc, exec, s[2:3]
	s_cbranch_vccnz .LBB0_256
	v_ashrrev_i32_e32 v145, 31, v144
	v_cvt_pk_bf16_f32 v124, v118, v119
	v_cvt_pk_bf16_f32 v125, v120, v121
	v_lshl_add_u64 v[128:129], v[144:145], 1, v[152:153]
	v_lshlrev_b32_e32 v134, 2, v147
	global_store_dwordx2 v[128:129], v[124:125], off offset:256
	v_and_b32_e32 v122, 0x1ec, v123
	v_lshl_add_u64 v[124:125], s[84:85], 0, v[134:135]
	v_lshl_add_u64 v[124:125], v[124:125], 0, v[148:149]
	v_lshlrev_b32_e32 v134, 2, v122
	v_lshl_add_u64 v[124:125], v[124:125], 0, v[134:135]
	global_store_dwordx4 v[124:125], v[118:121], off

.LBB0_260:
	s_andn2_b64 vcc, exec, s[2:3]
	s_cbranch_vccnz .LBB0_262
	v_ashrrev_i32_e32 v145, 31, v144
	v_cvt_pk_bf16_f32 v118, v114, v115
	v_cvt_pk_bf16_f32 v119, v116, v117
	v_lshl_add_u64 v[120:121], v[144:145], 1, v[152:153]
	v_lshlrev_b32_e32 v134, 2, v147
	global_store_dwordx2 v[120:121], v[118:119], off offset:288
	v_and_b32_e32 v120, 0x1fc, v122
	v_lshl_add_u64 v[118:119], s[84:85], 0, v[134:135]
	v_lshl_add_u64 v[118:119], v[118:119], 0, v[148:149]
	v_lshlrev_b32_e32 v134, 2, v120
	v_lshl_add_u64 v[118:119], v[118:119], 0, v[134:135]
	global_store_dwordx4 v[118:119], v[114:117], off

.LBB0_274:
	s_andn2_b64 vcc, exec, s[2:3]
	s_cbranch_vccnz .LBB0_276
	v_lshl_add_u64 v[148:149], s[94:95], 0, v[120:121]
	v_ashrrev_i32_e32 v145, 31, v144
	v_cvt_pk_bf16_f32 v128, v110, v111
	v_cvt_pk_bf16_f32 v129, v112, v113
	v_lshl_add_u64 v[148:149], v[144:145], 1, v[148:149]
	v_lshlrev_b32_e32 v134, 2, v124
	global_store_dwordx2 v[148:149], v[128:129], off
	v_and_b32_e32 v125, 0x16c, v144
	v_lshl_add_u64 v[128:129], s[84:85], 0, v[134:135]
	v_lshl_add_u64 v[128:129], v[128:129], 0, v[114:115]
	v_lshlrev_b32_e32 v134, 2, v125
	v_lshl_add_u64 v[128:129], v[128:129], 0, v[134:135]
	global_store_dwordx4 v[128:129], v[110:113], off

.LBB0_282:
	s_andn2_b64 vcc, exec, s[2:3]
	s_cbranch_vccnz .LBB0_284
	v_ashrrev_i32_e32 v145, 31, v144
	v_cvt_pk_bf16_f32 v110, v106, v107
	v_cvt_pk_bf16_f32 v111, v108, v109
	v_lshl_add_u64 v[112:113], v[144:145], 1, v[120:121]
	v_lshlrev_b32_e32 v134, 2, v124
	global_store_dwordx2 v[112:113], v[110:111], off offset:32
	v_and_b32_e32 v112, 0x17c, v126
	v_lshl_add_u64 v[110:111], s[84:85], 0, v[134:135]
	v_lshl_add_u64 v[110:111], v[110:111], 0, v[114:115]
	v_lshlrev_b32_e32 v134, 2, v112
	v_lshl_add_u64 v[110:111], v[110:111], 0, v[134:135]
	global_store_dwordx4 v[110:111], v[106:109], off

.LBB0_290:
	s_andn2_b64 vcc, exec, s[2:3]
	s_cbranch_vccnz .LBB0_292
	v_ashrrev_i32_e32 v145, 31, v144
	v_cvt_pk_bf16_f32 v106, v102, v103
	v_cvt_pk_bf16_f32 v107, v104, v105
	v_lshl_add_u64 v[108:109], v[144:145], 1, v[120:121]
	v_lshlrev_b32_e32 v134, 2, v124
	global_store_dwordx2 v[108:109], v[106:107], off offset:256
	v_and_b32_e32 v108, 0x1ec, v123
	v_lshl_add_u64 v[106:107], s[84:85], 0, v[134:135]
	v_lshl_add_u64 v[106:107], v[106:107], 0, v[114:115]
	v_lshlrev_b32_e32 v134, 2, v108
	v_lshl_add_u64 v[106:107], v[106:107], 0, v[134:135]
	global_store_dwordx4 v[106:107], v[102:105], off

.LBB0_298:
	s_andn2_b64 vcc, exec, s[2:3]
	s_cbranch_vccnz .LBB0_300
	v_ashrrev_i32_e32 v145, 31, v144
	v_cvt_pk_bf16_f32 v102, v98, v99
	v_cvt_pk_bf16_f32 v103, v100, v101
	v_lshl_add_u64 v[104:105], v[144:145], 1, v[120:121]
	v_lshlrev_b32_e32 v134, 2, v124
	global_store_dwordx2 v[104:105], v[102:103], off offset:288
	v_and_b32_e32 v104, 0x1fc, v122
	v_lshl_add_u64 v[102:103], s[84:85], 0, v[134:135]
	v_lshl_add_u64 v[102:103], v[102:103], 0, v[114:115]
	v_lshlrev_b32_e32 v134, 2, v104
	v_lshl_add_u64 v[102:103], v[102:103], 0, v[134:135]
	global_store_dwordx4 v[102:103], v[98:101], off

.LBB0_312:
	s_andn2_b64 vcc, exec, s[2:3]
	s_cbranch_vccnz .LBB0_314
	v_lshl_add_u64 v[108:109], s[94:95], 0, v[102:103]
	v_ashrrev_i32_e32 v145, 31, v144
	v_cvt_pk_bf16_f32 v106, v94, v95
	v_cvt_pk_bf16_f32 v107, v96, v97
	v_lshl_add_u64 v[108:109], v[144:145], 1, v[108:109]
	v_lshlrev_b32_e32 v134, 2, v104
	global_store_dwordx2 v[108:109], v[106:107], off
	v_and_b32_e32 v105, 0x16c, v144
	v_lshl_add_u64 v[106:107], s[84:85], 0, v[134:135]
	v_lshl_add_u64 v[106:107], v[106:107], 0, v[98:99]
	v_lshlrev_b32_e32 v134, 2, v105
	v_lshl_add_u64 v[106:107], v[106:107], 0, v[134:135]
	global_store_dwordx4 v[106:107], v[94:97], off

.LBB0_318:
	s_andn2_b64 vcc, exec, s[2:3]
	s_cbranch_vccnz .LBB0_320
	v_ashrrev_i32_e32 v145, 31, v144
	v_cvt_pk_bf16_f32 v94, v90, v91
	v_cvt_pk_bf16_f32 v95, v92, v93
	v_lshl_add_u64 v[96:97], v[144:145], 1, v[102:103]
	v_lshlrev_b32_e32 v134, 2, v104
	global_store_dwordx2 v[96:97], v[94:95], off offset:32
	v_and_b32_e32 v96, 0x17c, v126
	v_lshl_add_u64 v[94:95], s[84:85], 0, v[134:135]
	v_lshl_add_u64 v[94:95], v[94:95], 0, v[98:99]
	v_lshlrev_b32_e32 v134, 2, v96
	v_lshl_add_u64 v[94:95], v[94:95], 0, v[134:135]
	global_store_dwordx4 v[94:95], v[90:93], off

.LBB0_324:
	s_andn2_b64 vcc, exec, s[2:3]
	s_cbranch_vccnz .LBB0_326
	v_ashrrev_i32_e32 v145, 31, v144
	v_cvt_pk_bf16_f32 v90, v86, v87
	v_cvt_pk_bf16_f32 v91, v88, v89
	v_lshl_add_u64 v[92:93], v[144:145], 1, v[102:103]
	v_lshlrev_b32_e32 v134, 2, v104
	global_store_dwordx2 v[92:93], v[90:91], off offset:256
	v_and_b32_e32 v92, 0x1ec, v123
	v_lshl_add_u64 v[90:91], s[84:85], 0, v[134:135]
	v_lshl_add_u64 v[90:91], v[90:91], 0, v[98:99]
	v_lshlrev_b32_e32 v134, 2, v92
	v_lshl_add_u64 v[90:91], v[90:91], 0, v[134:135]
	global_store_dwordx4 v[90:91], v[86:89], off

.LBB0_330:
	s_andn2_b64 vcc, exec, s[2:3]
	s_cbranch_vccnz .LBB0_332
	v_ashrrev_i32_e32 v145, 31, v144
	v_cvt_pk_bf16_f32 v86, v82, v83
	v_cvt_pk_bf16_f32 v87, v84, v85
	v_lshl_add_u64 v[88:89], v[144:145], 1, v[102:103]
	v_lshlrev_b32_e32 v134, 2, v104
	global_store_dwordx2 v[88:89], v[86:87], off offset:288
	v_and_b32_e32 v88, 0x1fc, v122
	v_lshl_add_u64 v[86:87], s[84:85], 0, v[134:135]
	v_lshl_add_u64 v[86:87], v[86:87], 0, v[98:99]
	v_lshlrev_b32_e32 v134, 2, v88
	v_lshl_add_u64 v[86:87], v[86:87], 0, v[134:135]
	global_store_dwordx4 v[86:87], v[82:85], off

.LBB0_352:
	s_andn2_b64 vcc, exec, s[2:3]
	s_cbranch_vccnz .LBB0_354
	v_lshl_add_u64 v[96:97], s[94:95], 0, v[90:91]
	v_ashrrev_i32_e32 v145, 31, v144
	v_cvt_pk_bf16_f32 v94, v78, v79
	v_cvt_pk_bf16_f32 v95, v80, v81
	v_lshl_add_u64 v[96:97], v[144:145], 1, v[96:97]
	v_lshlrev_b32_e32 v134, 2, v92
	global_store_dwordx2 v[96:97], v[94:95], off
	v_and_b32_e32 v93, 0x16c, v144
	v_lshl_add_u64 v[94:95], s[84:85], 0, v[134:135]
	v_lshl_add_u64 v[94:95], v[94:95], 0, v[82:83]
	v_lshlrev_b32_e32 v134, 2, v93
	v_lshl_add_u64 v[94:95], v[94:95], 0, v[134:135]
	global_store_dwordx4 v[94:95], v[78:81], off

.LBB0_366:
	s_andn2_b64 vcc, exec, s[2:3]
	s_cbranch_vccnz .LBB0_368
	v_ashrrev_i32_e32 v145, 31, v144
	v_cvt_pk_bf16_f32 v78, v74, v75
	v_cvt_pk_bf16_f32 v79, v76, v77
	v_lshl_add_u64 v[80:81], v[144:145], 1, v[90:91]
	v_lshlrev_b32_e32 v134, 2, v92
	global_store_dwordx2 v[80:81], v[78:79], off offset:32
	v_and_b32_e32 v80, 0x17c, v126
	v_lshl_add_u64 v[78:79], s[84:85], 0, v[134:135]
	v_lshl_add_u64 v[78:79], v[78:79], 0, v[82:83]
	v_lshlrev_b32_e32 v134, 2, v80
	v_lshl_add_u64 v[78:79], v[78:79], 0, v[134:135]
	global_store_dwordx4 v[78:79], v[74:77], off

.LBB0_380:
	s_andn2_b64 vcc, exec, s[2:3]
	s_cbranch_vccnz .LBB0_382
	v_ashrrev_i32_e32 v145, 31, v144
	v_cvt_pk_bf16_f32 v74, v70, v71
	v_cvt_pk_bf16_f32 v75, v72, v73
	v_lshl_add_u64 v[76:77], v[144:145], 1, v[90:91]
	v_lshlrev_b32_e32 v134, 2, v92
	global_store_dwordx2 v[76:77], v[74:75], off offset:256
	v_and_b32_e32 v76, 0x1ec, v123
	v_lshl_add_u64 v[74:75], s[84:85], 0, v[134:135]
	v_lshl_add_u64 v[74:75], v[74:75], 0, v[82:83]
	v_lshlrev_b32_e32 v134, 2, v76
	v_lshl_add_u64 v[74:75], v[74:75], 0, v[134:135]
	global_store_dwordx4 v[74:75], v[70:73], off

.LBB0_394:
	s_andn2_b64 vcc, exec, s[2:3]
	s_cbranch_vccnz .LBB0_396
	v_ashrrev_i32_e32 v145, 31, v144
	v_cvt_pk_bf16_f32 v70, v66, v67
	v_cvt_pk_bf16_f32 v71, v68, v69
	v_lshl_add_u64 v[72:73], v[144:145], 1, v[90:91]
	v_lshlrev_b32_e32 v134, 2, v92
	global_store_dwordx2 v[72:73], v[70:71], off offset:288
	v_and_b32_e32 v72, 0x1fc, v122
	v_lshl_add_u64 v[70:71], s[84:85], 0, v[134:135]
	v_lshl_add_u64 v[70:71], v[70:71], 0, v[82:83]
	v_lshlrev_b32_e32 v134, 2, v72
	v_lshl_add_u64 v[70:71], v[70:71], 0, v[134:135]
	global_store_dwordx4 v[70:71], v[66:69], off

.LBB0_408:
	s_andn2_b64 vcc, exec, s[2:3]
	s_cbranch_vccnz .LBB0_410
	v_lshl_add_u64 v[76:77], s[94:95], 0, v[72:73]
	v_ashrrev_i32_e32 v145, 31, v144
	v_cvt_pk_bf16_f32 v74, v62, v63
	v_cvt_pk_bf16_f32 v75, v64, v65
	v_lshl_add_u64 v[76:77], v[144:145], 1, v[76:77]
	v_lshlrev_b32_e32 v134, 2, v67
	global_store_dwordx2 v[76:77], v[74:75], off
	v_and_b32_e32 v76, 0x16c, v144
	v_lshl_add_u64 v[74:75], s[84:85], 0, v[134:135]
	v_lshl_add_u64 v[74:75], v[74:75], 0, v[68:69]
	v_lshlrev_b32_e32 v134, 2, v76
	v_lshl_add_u64 v[74:75], v[74:75], 0, v[134:135]
	global_store_dwordx4 v[74:75], v[62:65], off

.LBB0_414:
	s_andn2_b64 vcc, exec, s[2:3]
	s_cbranch_vccnz .LBB0_416
	v_ashrrev_i32_e32 v145, 31, v144
	v_cvt_pk_bf16_f32 v62, v58, v59
	v_cvt_pk_bf16_f32 v63, v60, v61
	v_lshl_add_u64 v[64:65], v[144:145], 1, v[72:73]
	v_lshlrev_b32_e32 v134, 2, v67
	global_store_dwordx2 v[64:65], v[62:63], off offset:32
	v_and_b32_e32 v64, 0x17c, v126
	v_lshl_add_u64 v[62:63], s[84:85], 0, v[134:135]
	v_lshl_add_u64 v[62:63], v[62:63], 0, v[68:69]
	v_lshlrev_b32_e32 v134, 2, v64
	v_lshl_add_u64 v[62:63], v[62:63], 0, v[134:135]
	global_store_dwordx4 v[62:63], v[58:61], off

.LBB0_420:
	s_andn2_b64 vcc, exec, s[2:3]
	s_cbranch_vccnz .LBB0_422
	v_ashrrev_i32_e32 v145, 31, v144
	v_cvt_pk_bf16_f32 v58, v54, v55
	v_cvt_pk_bf16_f32 v59, v56, v57
	v_lshl_add_u64 v[60:61], v[144:145], 1, v[72:73]
	v_lshlrev_b32_e32 v134, 2, v67
	global_store_dwordx2 v[60:61], v[58:59], off offset:256
	v_and_b32_e32 v60, 0x1ec, v123
	v_lshl_add_u64 v[58:59], s[84:85], 0, v[134:135]
	v_lshl_add_u64 v[58:59], v[58:59], 0, v[68:69]
	v_lshlrev_b32_e32 v134, 2, v60
	v_lshl_add_u64 v[58:59], v[58:59], 0, v[134:135]
	global_store_dwordx4 v[58:59], v[54:57], off

.LBB0_426:
	s_andn2_b64 vcc, exec, s[2:3]
	s_cbranch_vccnz .LBB0_428
	v_ashrrev_i32_e32 v145, 31, v144
	v_cvt_pk_bf16_f32 v54, v50, v51
	v_cvt_pk_bf16_f32 v55, v52, v53
	v_lshl_add_u64 v[56:57], v[144:145], 1, v[72:73]
	v_lshlrev_b32_e32 v134, 2, v67
	global_store_dwordx2 v[56:57], v[54:55], off offset:288
	v_and_b32_e32 v56, 0x1fc, v122
	v_lshl_add_u64 v[54:55], s[84:85], 0, v[134:135]
	v_lshl_add_u64 v[54:55], v[54:55], 0, v[68:69]
	v_lshlrev_b32_e32 v134, 2, v56
	v_lshl_add_u64 v[54:55], v[54:55], 0, v[134:135]
	global_store_dwordx4 v[54:55], v[50:53], off

.LBB0_442:
	s_andn2_b64 vcc, exec, s[2:3]
	s_cbranch_vccnz .LBB0_444
	v_lshl_add_u64 v[62:63], s[94:95], 0, v[56:57]
	v_ashrrev_i32_e32 v145, 31, v144
	v_cvt_pk_bf16_f32 v60, v46, v47
	v_cvt_pk_bf16_f32 v61, v48, v49
	v_lshl_add_u64 v[62:63], v[144:145], 1, v[62:63]
	v_lshlrev_b32_e32 v134, 2, v58
	global_store_dwordx2 v[62:63], v[60:61], off
	v_and_b32_e32 v59, 0x16c, v144
	v_lshl_add_u64 v[60:61], s[84:85], 0, v[134:135]
	v_lshl_add_u64 v[60:61], v[60:61], 0, v[50:51]
	v_lshlrev_b32_e32 v134, 2, v59
	v_lshl_add_u64 v[60:61], v[60:61], 0, v[134:135]
	global_store_dwordx4 v[60:61], v[46:49], off

.LBB0_450:
	s_andn2_b64 vcc, exec, s[2:3]
	s_cbranch_vccnz .LBB0_452
	v_ashrrev_i32_e32 v145, 31, v144
	v_cvt_pk_bf16_f32 v46, v42, v43
	v_cvt_pk_bf16_f32 v47, v44, v45
	v_lshl_add_u64 v[48:49], v[144:145], 1, v[56:57]
	v_lshlrev_b32_e32 v134, 2, v58
	global_store_dwordx2 v[48:49], v[46:47], off offset:32
	v_and_b32_e32 v48, 0x17c, v126
	v_lshl_add_u64 v[46:47], s[84:85], 0, v[134:135]
	v_lshl_add_u64 v[46:47], v[46:47], 0, v[50:51]
	v_lshlrev_b32_e32 v134, 2, v48
	v_lshl_add_u64 v[46:47], v[46:47], 0, v[134:135]
	global_store_dwordx4 v[46:47], v[42:45], off

.LBB0_458:
	s_andn2_b64 vcc, exec, s[2:3]
	s_cbranch_vccnz .LBB0_460
	v_ashrrev_i32_e32 v145, 31, v144
	v_cvt_pk_bf16_f32 v42, v38, v39
	v_cvt_pk_bf16_f32 v43, v40, v41
	v_lshl_add_u64 v[44:45], v[144:145], 1, v[56:57]
	v_lshlrev_b32_e32 v134, 2, v58
	global_store_dwordx2 v[44:45], v[42:43], off offset:256
	v_and_b32_e32 v44, 0x1ec, v123
	v_lshl_add_u64 v[42:43], s[84:85], 0, v[134:135]
	v_lshl_add_u64 v[42:43], v[42:43], 0, v[50:51]
	v_lshlrev_b32_e32 v134, 2, v44
	v_lshl_add_u64 v[42:43], v[42:43], 0, v[134:135]
	global_store_dwordx4 v[42:43], v[38:41], off

.LBB0_466:
	s_andn2_b64 vcc, exec, s[2:3]
	s_cbranch_vccnz .LBB0_468
	v_ashrrev_i32_e32 v145, 31, v144
	v_cvt_pk_bf16_f32 v38, v34, v35
	v_cvt_pk_bf16_f32 v39, v36, v37
	v_lshl_add_u64 v[40:41], v[144:145], 1, v[56:57]
	v_lshlrev_b32_e32 v134, 2, v58
	global_store_dwordx2 v[40:41], v[38:39], off offset:288
	v_and_b32_e32 v40, 0x1fc, v122
	v_lshl_add_u64 v[38:39], s[84:85], 0, v[134:135]
	v_lshl_add_u64 v[38:39], v[38:39], 0, v[50:51]
	v_lshlrev_b32_e32 v134, 2, v40
	v_lshl_add_u64 v[38:39], v[38:39], 0, v[134:135]
	global_store_dwordx4 v[38:39], v[34:37], off

.LBB0_480:
	s_andn2_b64 vcc, exec, s[2:3]
	s_cbranch_vccnz .LBB0_482
	v_lshl_add_u64 v[44:45], s[94:95], 0, v[38:39]
	v_ashrrev_i32_e32 v145, 31, v144
	v_cvt_pk_bf16_f32 v42, v30, v31
	v_cvt_pk_bf16_f32 v43, v32, v33
	v_lshl_add_u64 v[44:45], v[144:145], 1, v[44:45]
	v_lshlrev_b32_e32 v134, 2, v40
	global_store_dwordx2 v[44:45], v[42:43], off
	v_and_b32_e32 v41, 0x16c, v144
	v_lshl_add_u64 v[42:43], s[84:85], 0, v[134:135]
	v_lshl_add_u64 v[42:43], v[42:43], 0, v[34:35]
	v_lshlrev_b32_e32 v134, 2, v41
	v_lshl_add_u64 v[42:43], v[42:43], 0, v[134:135]
	global_store_dwordx4 v[42:43], v[30:33], off

.LBB0_486:
	s_andn2_b64 vcc, exec, s[2:3]
	s_cbranch_vccnz .LBB0_488
	v_ashrrev_i32_e32 v145, 31, v144
	v_cvt_pk_bf16_f32 v30, v26, v27
	v_cvt_pk_bf16_f32 v31, v28, v29
	v_lshl_add_u64 v[32:33], v[144:145], 1, v[38:39]
	v_lshlrev_b32_e32 v134, 2, v40
	global_store_dwordx2 v[32:33], v[30:31], off offset:32
	v_and_b32_e32 v32, 0x17c, v126
	v_lshl_add_u64 v[30:31], s[84:85], 0, v[134:135]
	v_lshl_add_u64 v[30:31], v[30:31], 0, v[34:35]
	v_lshlrev_b32_e32 v134, 2, v32
	v_lshl_add_u64 v[30:31], v[30:31], 0, v[134:135]
	global_store_dwordx4 v[30:31], v[26:29], off

.LBB0_492:
	s_andn2_b64 vcc, exec, s[2:3]
	s_cbranch_vccnz .LBB0_494
	v_ashrrev_i32_e32 v145, 31, v144
	v_cvt_pk_bf16_f32 v26, v22, v23
	v_cvt_pk_bf16_f32 v27, v24, v25
	v_lshl_add_u64 v[28:29], v[144:145], 1, v[38:39]
	v_lshlrev_b32_e32 v134, 2, v40
	global_store_dwordx2 v[28:29], v[26:27], off offset:256
	v_and_b32_e32 v28, 0x1ec, v123
	v_lshl_add_u64 v[26:27], s[84:85], 0, v[134:135]
	v_lshl_add_u64 v[26:27], v[26:27], 0, v[34:35]
	v_lshlrev_b32_e32 v134, 2, v28
	v_lshl_add_u64 v[26:27], v[26:27], 0, v[134:135]
	global_store_dwordx4 v[26:27], v[22:25], off

.LBB0_498:
	s_andn2_b64 vcc, exec, s[2:3]
	s_cbranch_vccnz .LBB0_500
	v_ashrrev_i32_e32 v145, 31, v144
	v_cvt_pk_bf16_f32 v22, v18, v19
	v_cvt_pk_bf16_f32 v23, v20, v21
	v_lshl_add_u64 v[24:25], v[144:145], 1, v[38:39]
	v_lshlrev_b32_e32 v134, 2, v40
	global_store_dwordx2 v[24:25], v[22:23], off offset:288
	v_and_b32_e32 v24, 0x1fc, v122
	v_lshl_add_u64 v[22:23], s[84:85], 0, v[134:135]
	v_lshl_add_u64 v[22:23], v[22:23], 0, v[34:35]
	v_lshlrev_b32_e32 v134, 2, v24
	v_lshl_add_u64 v[22:23], v[22:23], 0, v[134:135]
	global_store_dwordx4 v[22:23], v[18:21], off

.LBB0_520:
	s_andn2_b64 vcc, exec, s[2:3]
	s_cbranch_vccnz .LBB0_522
	v_lshl_add_u64 v[32:33], s[94:95], 0, v[26:27]
	v_ashrrev_i32_e32 v145, 31, v144
	v_cvt_pk_bf16_f32 v30, v14, v15
	v_cvt_pk_bf16_f32 v31, v16, v17
	v_lshl_add_u64 v[32:33], v[144:145], 1, v[32:33]
	v_lshlrev_b32_e32 v134, 2, v28
	global_store_dwordx2 v[32:33], v[30:31], off
	v_lshl_add_u64 v[30:31], s[84:85], 0, v[134:135]
	v_lshl_add_u64 v[30:31], v[30:31], 0, v[18:19]
	v_lshlrev_b32_e32 v134, 2, v29
	v_lshl_add_u64 v[30:31], v[30:31], 0, v[134:135]
	global_store_dwordx4 v[30:31], v[14:17], off

.LBB0_534:
	s_andn2_b64 vcc, exec, s[2:3]
	s_cbranch_vccnz .LBB0_536
	v_ashrrev_i32_e32 v145, 31, v144
	v_cvt_pk_bf16_f32 v16, v10, v11
	v_cvt_pk_bf16_f32 v17, v12, v13
	v_lshl_add_u64 v[30:31], v[144:145], 1, v[26:27]
	v_lshlrev_b32_e32 v134, 2, v28
	global_store_dwordx2 v[30:31], v[16:17], off offset:32
	v_lshl_add_u64 v[16:17], s[84:85], 0, v[134:135]
	v_lshl_add_u64 v[16:17], v[16:17], 0, v[18:19]
	v_lshlrev_b32_e32 v134, 2, v14
	v_lshl_add_u64 v[14:15], v[16:17], 0, v[134:135]
	global_store_dwordx4 v[14:15], v[10:13], off

.LBB0_548:
	s_andn2_b64 vcc, exec, s[2:3]
	s_cbranch_vccnz .LBB0_550
	v_ashrrev_i32_e32 v145, 31, v144
	v_cvt_pk_bf16_f32 v12, v6, v7
	v_cvt_pk_bf16_f32 v13, v8, v9
	v_lshl_add_u64 v[14:15], v[144:145], 1, v[26:27]
	v_lshlrev_b32_e32 v134, 2, v28
	global_store_dwordx2 v[14:15], v[12:13], off offset:256
	v_lshl_add_u64 v[12:13], s[84:85], 0, v[134:135]
	v_lshl_add_u64 v[12:13], v[12:13], 0, v[18:19]
	v_lshlrev_b32_e32 v134, 2, v10
	v_lshl_add_u64 v[10:11], v[12:13], 0, v[134:135]
	global_store_dwordx4 v[10:11], v[6:9], off

.LBB0_562:
	s_andn2_b64 vcc, exec, s[2:3]
	s_cbranch_vccnz .LBB0_564
	v_ashrrev_i32_e32 v145, 31, v144
	v_cvt_pk_bf16_f32 v8, v2, v3
	v_cvt_pk_bf16_f32 v9, v4, v5
	v_lshl_add_u64 v[10:11], v[144:145], 1, v[26:27]
	v_lshlrev_b32_e32 v134, 2, v28
	global_store_dwordx2 v[10:11], v[8:9], off offset:288
	v_lshl_add_u64 v[8:9], s[84:85], 0, v[134:135]
	v_lshl_add_u64 v[8:9], v[8:9], 0, v[18:19]
	v_lshlrev_b32_e32 v134, 2, v6
	v_lshl_add_u64 v[6:7], v[8:9], 0, v[134:135]
	global_store_dwordx4 v[6:7], v[2:5], off

.LBB0_579:
	s_lshr_b32 s6, s15, 2
	s_and_b32 s3, s15, 7
	s_and_b32 s2, s12, 0xc0
	s_and_b32 s6, s6, 0x3fffff8
	s_bitset1_b32 s2, 14
	s_or_b32 s3, s6, s3
	s_lshl_b32 s3, s3, 6
	v_add_lshl_u32 v10, s2, v1, 11
	v_lshl_add_u64 v[24:25], v[12:13], 0, v[10:11]
	v_add_lshl_u32 v10, s3, v1, 11
	v_lshl_add_u64 v[116:117], v[14:15], 0, v[10:11]
	global_load_dwordx4 v[2:5], v[24:25], off
	global_load_dwordx4 v[6:9], v[24:25], off offset:128
	global_load_dwordx4 v[16:19], v[116:117], off
	global_load_dwordx4 v[20:23], v[116:117], off offset:128
	global_load_dwordx4 v[36:39], v[24:25], off offset:256
	global_load_dwordx4 v[40:43], v[24:25], off offset:384
	global_load_dwordx4 v[44:47], v[116:117], off offset:256
	global_load_dwordx4 v[48:51], v[116:117], off offset:384
	global_load_dwordx4 v[52:55], v[24:25], off offset:512
	global_load_dwordx4 v[56:59], v[24:25], off offset:640
	global_load_dwordx4 v[60:63], v[116:117], off offset:512
	global_load_dwordx4 v[64:67], v[116:117], off offset:640
	global_load_dwordx4 v[68:71], v[24:25], off offset:768
	global_load_dwordx4 v[72:75], v[24:25], off offset:896
	global_load_dwordx4 v[76:79], v[116:117], off offset:768
	global_load_dwordx4 v[80:83], v[116:117], off offset:896
	s_mov_b64 s[10:11], -1
	s_waitcnt vmcnt(0)
	ds_write_b128 v26, v[2:5]
	ds_write_b128 v26, v[6:9] offset:128
	ds_write_b128 v26, v[16:19] offset:34816
	ds_write_b128 v26, v[20:23] offset:34944
	s_waitcnt lgkmcnt(0)
	s_barrier
	ds_read_b128 v[2:5], v33 offset:34816
	ds_read_b128 v[6:9], v33 offset:43520
	ds_read_b128 v[16:19], v28
	ds_read_b128 v[20:23], v28 offset:64
	ds_read_b128 v[84:87], v33 offset:34880
	global_load_dwordx4 v[88:91], v[24:25], off offset:1024
	global_load_dwordx4 v[92:95], v[24:25], off offset:1152
	ds_read_b128 v[96:99], v33 offset:43584
	s_waitcnt lgkmcnt(3)
	v_mfma_f32_16x16x32_bf16 v[2:5], v[2:5], v[16:19], 0
	v_mfma_f32_16x16x32_bf16 v[6:9], v[6:9], v[16:19], 0
	global_load_dwordx4 v[16:19], v[116:117], off offset:1024
	global_load_dwordx4 v[100:103], v[116:117], off offset:1152
	ds_read_b128 v[104:107], v33 offset:34944
	s_waitcnt lgkmcnt(2)
	v_mfma_f32_16x16x32_bf16 v[2:5], v[84:87], v[20:23], v[2:5]
	ds_read_b128 v[84:87], v33 offset:43648
	ds_read_b128 v[108:111], v28 offset:128
	ds_read_b128 v[112:115], v28 offset:192
	s_waitcnt lgkmcnt(4)
	v_mfma_f32_16x16x32_bf16 v[6:9], v[96:99], v[20:23], v[6:9]
	ds_read_b128 v[20:23], v33 offset:35008
	ds_read_b128 v[96:99], v33 offset:43712
	ds_write_b128 v26, v[36:39] offset:17408
	ds_write_b128 v26, v[40:43] offset:17536
	ds_write_b128 v26, v[44:47] offset:52224
	ds_write_b128 v26, v[48:51] offset:52352
	s_waitcnt lgkmcnt(7)
	v_mfma_f32_16x16x32_bf16 v[2:5], v[104:107], v[108:111], v[2:5]
	s_waitcnt lgkmcnt(0)
	s_barrier
	v_mfma_f32_16x16x32_bf16 v[6:9], v[84:87], v[108:111], v[6:9]
	v_mfma_f32_16x16x32_bf16 v[2:5], v[20:23], v[112:115], v[2:5]
	ds_read_b128 v[20:23], v30 offset:52224
	ds_read_b128 v[36:39], v30 offset:60928
	ds_read_b128 v[40:43], v29
	ds_read_b128 v[44:47], v29 offset:64
	ds_read_b128 v[48:51], v30 offset:52288
	v_mfma_f32_16x16x32_bf16 v[6:9], v[96:99], v[112:115], v[6:9]
	s_waitcnt lgkmcnt(2)
	v_mfma_f32_16x16x32_bf16 v[2:5], v[20:23], v[40:43], v[2:5]
	global_load_dwordx4 v[20:23], v[24:25], off offset:1280
	global_load_dwordx4 v[84:87], v[24:25], off offset:1408
	ds_read_b128 v[96:99], v30 offset:60992
	v_mfma_f32_16x16x32_bf16 v[6:9], v[36:39], v[40:43], v[6:9]
	global_load_dwordx4 v[36:39], v[116:117], off offset:1280
	global_load_dwordx4 v[40:43], v[116:117], off offset:1408
	ds_read_b128 v[104:107], v30 offset:52352
	s_waitcnt lgkmcnt(2)
	v_mfma_f32_16x16x32_bf16 v[2:5], v[48:51], v[44:47], v[2:5]
	ds_read_b128 v[48:51], v30 offset:61056
	ds_read_b128 v[108:111], v29 offset:128
	ds_read_b128 v[112:115], v29 offset:192
	s_waitcnt lgkmcnt(4)
	v_mfma_f32_16x16x32_bf16 v[6:9], v[96:99], v[44:47], v[6:9]
	ds_read_b128 v[44:47], v30 offset:52416
	ds_read_b128 v[96:99], v30 offset:61120
	ds_write_b128 v26, v[52:55]
	ds_write_b128 v26, v[56:59] offset:128
	ds_write_b128 v26, v[60:63] offset:34816
	ds_write_b128 v26, v[64:67] offset:34944
	s_waitcnt lgkmcnt(7)
	v_mfma_f32_16x16x32_bf16 v[2:5], v[104:107], v[108:111], v[2:5]
	s_waitcnt lgkmcnt(0)
	s_barrier
	v_mfma_f32_16x16x32_bf16 v[6:9], v[48:51], v[108:111], v[6:9]
	v_mfma_f32_16x16x32_bf16 v[2:5], v[44:47], v[112:115], v[2:5]
	ds_read_b128 v[44:47], v33 offset:34816
	ds_read_b128 v[48:51], v33 offset:43520
	ds_read_b128 v[52:55], v28
	ds_read_b128 v[56:59], v28 offset:64
	ds_read_b128 v[60:63], v33 offset:34880
	v_mfma_f32_16x16x32_bf16 v[6:9], v[96:99], v[112:115], v[6:9]
	s_waitcnt lgkmcnt(2)
	v_mfma_f32_16x16x32_bf16 v[2:5], v[44:47], v[52:55], v[2:5]
	global_load_dwordx4 v[44:47], v[24:25], off offset:1536
	global_load_dwordx4 v[64:67], v[24:25], off offset:1664
	ds_read_b128 v[96:99], v33 offset:43584
	v_mfma_f32_16x16x32_bf16 v[6:9], v[48:51], v[52:55], v[6:9]
	global_load_dwordx4 v[48:51], v[116:117], off offset:1536
	global_load_dwordx4 v[52:55], v[116:117], off offset:1664
	ds_read_b128 v[104:107], v33 offset:34944
	s_waitcnt lgkmcnt(2)
	v_mfma_f32_16x16x32_bf16 v[2:5], v[60:63], v[56:59], v[2:5]
	ds_read_b128 v[60:63], v33 offset:43648
	ds_read_b128 v[108:111], v28 offset:128
	ds_read_b128 v[112:115], v28 offset:192
	s_waitcnt lgkmcnt(4)
	v_mfma_f32_16x16x32_bf16 v[6:9], v[96:99], v[56:59], v[6:9]
	ds_read_b128 v[56:59], v33 offset:35008
	ds_read_b128 v[96:99], v33 offset:43712
	ds_write_b128 v26, v[68:71] offset:17408
	ds_write_b128 v26, v[72:75] offset:17536
	ds_write_b128 v26, v[76:79] offset:52224
	ds_write_b128 v26, v[80:83] offset:52352
	s_waitcnt lgkmcnt(7)
	v_mfma_f32_16x16x32_bf16 v[2:5], v[104:107], v[108:111], v[2:5]
	s_waitcnt lgkmcnt(0)
	s_barrier
	v_mfma_f32_16x16x32_bf16 v[2:5], v[56:59], v[112:115], v[2:5]
	ds_read_b128 v[56:59], v30 offset:52224
	v_mfma_f32_16x16x32_bf16 v[6:9], v[60:63], v[108:111], v[6:9]
	ds_read_b128 v[60:63], v29
	ds_read_b128 v[68:71], v29 offset:64
	ds_read_b128 v[72:75], v30 offset:52288
	v_mfma_f32_16x16x32_bf16 v[6:9], v[96:99], v[112:115], v[6:9]
	s_waitcnt lgkmcnt(2)
	v_mfma_f32_16x16x32_bf16 v[2:5], v[56:59], v[60:63], v[2:5]
	ds_read_b128 v[56:59], v30 offset:60928
	ds_read_b128 v[76:79], v30 offset:60992
	s_waitcnt lgkmcnt(1)
	v_mfma_f32_16x16x32_bf16 v[6:9], v[56:59], v[60:63], v[6:9]
	ds_read_b128 v[56:59], v30 offset:52352
	v_mfma_f32_16x16x32_bf16 v[2:5], v[72:75], v[68:71], v[2:5]
	s_waitcnt lgkmcnt(1)
	v_mfma_f32_16x16x32_bf16 v[6:9], v[76:79], v[68:71], v[6:9]
	ds_read_b128 v[60:63], v29 offset:128
	ds_read_b128 v[68:71], v29 offset:192
	ds_read_b128 v[72:75], v30 offset:52416
	s_waitcnt lgkmcnt(2)
	v_mfma_f32_16x16x32_bf16 v[2:5], v[56:59], v[60:63], v[2:5]
	ds_read_b128 v[56:59], v30 offset:61056
	ds_read_b128 v[76:79], v30 offset:61120
	s_waitcnt lgkmcnt(1)
	v_mfma_f32_16x16x32_bf16 v[6:9], v[56:59], v[60:63], v[6:9]
	global_load_dwordx4 v[56:59], v[24:25], off offset:1792
	global_load_dwordx4 v[60:63], v[24:25], off offset:1920
	global_load_dwordx4 v[80:83], v[116:117], off offset:1792
	global_load_dwordx4 v[96:99], v[116:117], off offset:1920
	s_waitcnt vmcnt(15)
	ds_write_b128 v26, v[88:91]
	s_waitcnt vmcnt(14)
	ds_write_b128 v26, v[92:95] offset:128
	s_waitcnt vmcnt(13)
	ds_write_b128 v26, v[16:19] offset:34816
	s_waitcnt vmcnt(12)
	ds_write_b128 v26, v[100:103] offset:34944
	s_waitcnt lgkmcnt(0)
	s_barrier
	ds_read_b128 v[16:19], v33 offset:34816
	v_mfma_f32_16x16x32_bf16 v[2:5], v[72:75], v[68:71], v[2:5]
	v_mfma_f32_16x16x32_bf16 v[6:9], v[76:79], v[68:71], v[6:9]
	ds_read_b128 v[68:71], v28
	ds_read_b128 v[72:75], v28 offset:64
	ds_read_b128 v[76:79], v33 offset:34880
	s_waitcnt lgkmcnt(2)
	v_mfma_f32_16x16x32_bf16 v[2:5], v[16:19], v[68:71], v[2:5]
	ds_read_b128 v[16:19], v33 offset:43520
	ds_read_b128 v[88:91], v33 offset:43584
	s_waitcnt lgkmcnt(1)
	v_mfma_f32_16x16x32_bf16 v[6:9], v[16:19], v[68:71], v[6:9]
	ds_read_b128 v[16:19], v33 offset:34944
	v_mfma_f32_16x16x32_bf16 v[2:5], v[76:79], v[72:75], v[2:5]
	ds_read_b128 v[68:71], v33 offset:43648
	ds_read_b128 v[76:79], v28 offset:128
	ds_read_b128 v[92:95], v28 offset:192
	s_waitcnt lgkmcnt(4)
	v_mfma_f32_16x16x32_bf16 v[6:9], v[88:91], v[72:75], v[6:9]
	ds_read_b128 v[72:75], v33 offset:35008
	ds_read_b128 v[88:91], v33 offset:43712
	s_waitcnt vmcnt(11)
	ds_write_b128 v26, v[20:23] offset:17408
	s_waitcnt vmcnt(10)
	ds_write_b128 v26, v[84:87] offset:17536
	s_waitcnt vmcnt(9)
	ds_write_b128 v26, v[36:39] offset:52224
	s_waitcnt vmcnt(8)
	ds_write_b128 v26, v[40:43] offset:52352
	s_waitcnt lgkmcnt(7)
	v_mfma_f32_16x16x32_bf16 v[2:5], v[16:19], v[76:79], v[2:5]
	s_waitcnt lgkmcnt(0)
	s_barrier
	ds_read_b128 v[16:19], v30 offset:52224
	v_mfma_f32_16x16x32_bf16 v[6:9], v[68:71], v[76:79], v[6:9]
	ds_read_b128 v[20:23], v29
	ds_read_b128 v[36:39], v29 offset:64
	ds_read_b128 v[40:43], v30 offset:52288
	v_mfma_f32_16x16x32_bf16 v[2:5], v[72:75], v[92:95], v[2:5]
	v_mfma_f32_16x16x32_bf16 v[6:9], v[88:91], v[92:95], v[6:9]
	s_waitcnt lgkmcnt(2)
	v_mfma_f32_16x16x32_bf16 v[2:5], v[16:19], v[20:23], v[2:5]
	ds_read_b128 v[16:19], v30 offset:60928
	ds_read_b128 v[68:71], v30 offset:60992
	s_waitcnt lgkmcnt(1)
	v_mfma_f32_16x16x32_bf16 v[6:9], v[16:19], v[20:23], v[6:9]
	ds_read_b128 v[16:19], v30 offset:52352
	v_mfma_f32_16x16x32_bf16 v[2:5], v[40:43], v[36:39], v[2:5]
	s_waitcnt lgkmcnt(1)
	v_mfma_f32_16x16x32_bf16 v[6:9], v[68:71], v[36:39], v[6:9]
	ds_read_b128 v[20:23], v29 offset:128
	ds_read_b128 v[36:39], v29 offset:192
	ds_read_b128 v[40:43], v30 offset:52416
	s_waitcnt lgkmcnt(2)
	v_mfma_f32_16x16x32_bf16 v[2:5], v[16:19], v[20:23], v[2:5]
	ds_read_b128 v[16:19], v30 offset:61056
	ds_read_b128 v[68:71], v30 offset:61120
	s_waitcnt vmcnt(7)
	ds_write_b128 v26, v[44:47]
	s_waitcnt vmcnt(6)
	ds_write_b128 v26, v[64:67] offset:128
	s_waitcnt vmcnt(5)
	ds_write_b128 v26, v[48:51] offset:34816
	s_waitcnt vmcnt(4)
	ds_write_b128 v26, v[52:55] offset:34944
	s_waitcnt lgkmcnt(0)
	v_mfma_f32_16x16x32_bf16 v[6:9], v[16:19], v[20:23], v[6:9]
	s_barrier
	ds_read_b128 v[16:19], v33 offset:34816
	v_mfma_f32_16x16x32_bf16 v[2:5], v[40:43], v[36:39], v[2:5]
	v_mfma_f32_16x16x32_bf16 v[6:9], v[68:71], v[36:39], v[6:9]
	ds_read_b128 v[20:23], v28
	ds_read_b128 v[36:39], v28 offset:64
	ds_read_b128 v[40:43], v33 offset:34880
	s_waitcnt lgkmcnt(2)
	v_mfma_f32_16x16x32_bf16 v[2:5], v[16:19], v[20:23], v[2:5]
	ds_read_b128 v[16:19], v33 offset:43520
	ds_read_b128 v[44:47], v33 offset:43584
	s_waitcnt lgkmcnt(1)
	v_mfma_f32_16x16x32_bf16 v[6:9], v[16:19], v[20:23], v[6:9]
	ds_read_b128 v[16:19], v33 offset:34944
	v_mfma_f32_16x16x32_bf16 v[2:5], v[40:43], v[36:39], v[2:5]
	s_waitcnt lgkmcnt(1)
	v_mfma_f32_16x16x32_bf16 v[6:9], v[44:47], v[36:39], v[6:9]
	ds_read_b128 v[20:23], v28 offset:128
	ds_read_b128 v[36:39], v28 offset:192
	ds_read_b128 v[40:43], v33 offset:35008
	s_waitcnt lgkmcnt(2)
	v_mfma_f32_16x16x32_bf16 v[2:5], v[16:19], v[20:23], v[2:5]
	ds_read_b128 v[16:19], v33 offset:43648
	ds_read_b128 v[44:47], v33 offset:43712
	s_waitcnt vmcnt(3)
	ds_write_b128 v26, v[56:59] offset:17408
	s_waitcnt vmcnt(2)
	ds_write_b128 v26, v[60:63] offset:17536
	s_waitcnt vmcnt(1)
	ds_write_b128 v26, v[80:83] offset:52224
	s_waitcnt vmcnt(0)
	ds_write_b128 v26, v[96:99] offset:52352
	s_waitcnt lgkmcnt(0)
	v_mfma_f32_16x16x32_bf16 v[6:9], v[16:19], v[20:23], v[6:9]
	s_barrier
	ds_read_b128 v[16:19], v30 offset:52224
	v_mfma_f32_16x16x32_bf16 v[2:5], v[40:43], v[36:39], v[2:5]
	v_mfma_f32_16x16x32_bf16 v[6:9], v[44:47], v[36:39], v[6:9]
	ds_read_b128 v[20:23], v29
	ds_read_b128 v[36:39], v29 offset:64
	ds_read_b128 v[40:43], v30 offset:52288
	s_waitcnt lgkmcnt(2)
	v_mfma_f32_16x16x32_bf16 v[2:5], v[16:19], v[20:23], v[2:5]
	ds_read_b128 v[16:19], v30 offset:60928
	ds_read_b128 v[44:47], v30 offset:60992
	s_waitcnt lgkmcnt(1)
	v_mfma_f32_16x16x32_bf16 v[6:9], v[16:19], v[20:23], v[6:9]
	ds_read_b128 v[16:19], v30 offset:52352
	v_mfma_f32_16x16x32_bf16 v[2:5], v[40:43], v[36:39], v[2:5]
	s_waitcnt lgkmcnt(1)
	v_mfma_f32_16x16x32_bf16 v[6:9], v[44:47], v[36:39], v[6:9]
	ds_read_b128 v[20:23], v29 offset:128
	ds_read_b128 v[36:39], v29 offset:192
	ds_read_b128 v[40:43], v30 offset:52416
	s_waitcnt lgkmcnt(2)
	v_mfma_f32_16x16x32_bf16 v[2:5], v[16:19], v[20:23], v[2:5]
	ds_read_b128 v[16:19], v30 offset:61056
	ds_read_b128 v[44:47], v30 offset:61120
	s_waitcnt lgkmcnt(0)
	s_barrier
	v_mfma_f32_16x16x32_bf16 v[16:19], v[16:19], v[20:23], v[6:9]
	v_mov_b32_e32 v23, v11
	v_mov_b32_e32 v21, v11
	v_mfma_f32_16x16x32_bf16 v[6:9], v[40:43], v[36:39], v[2:5]
	v_mfma_f32_16x16x32_bf16 v[2:5], v[44:47], v[36:39], v[16:19]
	s_nop 3
	v_add_u32_e32 v17, s2, v27
	s_lshr_b32 s2, s15, 5
	s_cmp_lg_u32 s2, 3
	s_cselect_b64 s[6:7], -1, 0
	v_mul_u32_u24_e32 v10, 0xc00, v17
	s_cmp_eq_u32 s2, 2
	v_lshl_add_u32 v22, v17, 11, v34
	v_lshlrev_b32_e32 v20, 10, v17
	v_add_u32_e32 v17, 0xffffc000, v17
	s_cselect_b32 s18, s14, 0x2047800
	v_lshrrev_b32_e32 v17, 5, v17
	s_cmp_gt_u32 s15, 31
	v_or_b32_e32 v16, s3, v31
	v_mad_u32_u24 v18, v17, 15, v32
	v_mov_b32_e32 v19, v11
	s_cselect_b64 s[2:3], -1, 0
	v_cndmask_b32_e64 v17, 0, 1, s[6:7]
	v_lshlrev_b64 v[18:19], 11, v[18:19]
	s_and_b64 vcc, exec, s[2:3]
	v_cmp_ne_u32_e64 s[6:7], 1, v17
	s_cbranch_vccz .LBB0_595
	s_and_b64 vcc, exec, s[6:7]
	v_and_b32_e32 v24, 0x1dc, v16
	s_cbranch_vccnz .LBB0_582
	s_lshl_b32 s10, s18, 2
	v_lshl_add_u64 v[38:39], s[94:95], 0, v[10:11]
	v_mov_b32_e32 v17, v11
	s_add_u32 s10, s84, s10
	v_cvt_pk_bf16_f32 v36, v6, v7
	v_cvt_pk_bf16_f32 v37, v8, v9
	v_lshl_add_u64 v[38:39], v[16:17], 1, v[38:39]
	s_addc_u32 s11, s85, 0
	global_store_dwordx2 v[38:39], v[36:37], off
	v_lshl_add_u64 v[36:37], s[10:11], 0, v[22:23]
	v_lshlrev_b32_e32 v38, 2, v24
	v_mov_b32_e32 v39, v11
	v_lshl_add_u64 v[36:37], v[36:37], 0, v[38:39]
	s_mov_b64 s[10:11], 0
	global_store_dwordx4 v[36:37], v[6:9], off

.LBB0_588:
	v_or_b32_e32 v6, 32, v16
	s_and_b64 vcc, exec, s[6:7]
	v_and_b32_e32 v6, 0x1fc, v6
	s_cbranch_vccnz .LBB0_590
	s_lshl_b32 s2, s18, 2
	v_mov_b32_e32 v17, v11
	s_add_u32 s2, s84, s2
	v_cvt_pk_bf16_f32 v8, v2, v3
	v_cvt_pk_bf16_f32 v9, v4, v5
	v_lshl_add_u64 v[36:37], v[16:17], 1, v[24:25]
	s_addc_u32 s3, s85, 0
	global_store_dwordx2 v[36:37], v[8:9], off offset:64
	v_lshl_add_u64 v[8:9], s[2:3], 0, v[22:23]
	v_lshlrev_b32_e32 v10, 2, v6
	v_lshl_add_u64 v[8:9], v[8:9], 0, v[10:11]
	s_mov_b64 s[2:3], 0
	global_store_dwordx4 v[8:9], v[2:5], off
